# grid barrier: last-arriving XCD leader releases every XCD's generation word directly (other leaders wait on their own word): one hop less
# speedup vs baseline: 1.0052x; 1.0052x over previous
; __device__ __forceinline__ unsigned xb_ld(unsigned* p)              { return __hip_atomic_load(p, __ATOMIC_RELAXED, __HIP_MEMORY_SCOPE_AGENT); }
; __device__ __forceinline__ unsigned xb_add(unsigned* p, unsigned v) { return __hip_atomic_fetch_add(p, v, __ATOMIC_RELAXED, __HIP_MEMORY_SCOPE_AGENT); }
; #define XB_SPIN(cond, bar) do { unsigned _sp = 0; while (cond) { __builtin_amdgcn_s_sleep(1); \
;     if ((++_sp & 255u) == 0u) { if (xb_ld(&(bar)[XB_TMO])) break; if (_sp > XB_SPIN_CAP) { atomicAdd(&(bar)[XB_TMO], 1u); break; } } } } while (0)
; __device__ __forceinline__ void xcd_barrier(const XcdBarrier& b) {
;     ...
;         unsigned nloc = b.st[0], nx = b.st[1];
;         if (nloc == 0u) { xcd_barrier_complete(bar, b.x, nloc, nx); b.st[0] = nloc; b.st[1] = nx; }
;         const unsigned old = xb_add(&bar[XB_XSUB(b.x)], 1u);
;         const unsigned gen = old / nloc;
;         if (old + 1u == (gen + 1u) * nloc) {
;             __builtin_amdgcn_fence(__ATOMIC_RELEASE, "agent");
;             asm volatile("s_waitcnt vmcnt(0)" ::: "memory");
;             const unsigned og = xb_add(&bar[XB_TOP], 1u);
;             const unsigned tg = og / nx;
;             if (og + 1u == (tg + 1u) * nx) xb_add(&bar[XB_TOPGEN], 1u);
;             else XB_SPIN(xb_ld(&bar[XB_TOPGEN]) == tg, bar);
;             __builtin_amdgcn_fence(__ATOMIC_ACQUIRE, "agent");
;             xb_add(&bar[XB_XGEN(b.x)], 1u);
;             asm volatile("s_waitcnt vmcnt(0)" ::: "memory");
;         } else {
;             XB_SPIN(xb_ld(&bar[XB_XGEN(b.x)]) == gen, bar);
.LBB0_66:
	s_or_b64 exec, exec, s[14:15]
	buffer_inv sc1
	v_cvt_f32_u32_e32 v4, v2
	s_waitcnt vmcnt(1)
	v_readfirstlane_b32 s4, v3
	v_sub_u32_e32 v3, 0, v2
	v_rcp_iflag_f32_e32 v4, v4
	v_add_u32_e32 v5, s4, v1
	v_mul_f32_e32 v4, 0x4f7ffffe, v4
	v_cvt_u32_f32_e32 v4, v4
	v_mul_lo_u32 v1, v3, v4
	v_mul_hi_u32 v1, v4, v1
	v_add_u32_e32 v1, v4, v1
	v_mul_hi_u32 v1, v5, v1
	v_mul_lo_u32 v3, v1, v2
	v_sub_u32_e32 v3, v5, v3
	v_add_u32_e32 v4, 1, v1
	v_cmp_ge_u32_e32 vcc, v3, v2
	s_nop 1
	v_cndmask_b32_e32 v1, v1, v4, vcc
	v_sub_u32_e32 v4, v3, v2
	v_cndmask_b32_e32 v3, v3, v4, vcc
	v_add_u32_e32 v4, 1, v1
	v_cmp_ge_u32_e32 vcc, v3, v2
	v_add_u32_e32 v3, 1, v5
	s_nop 0
	v_cndmask_b32_e32 v1, v1, v4, vcc
	v_mul_lo_u32 v4, v2, v1
	v_add_u32_e32 v2, v4, v2
	v_cmp_ne_u32_e32 vcc, v3, v2
	v_mov_b32_e32 v250, v1
	s_and_saveexec_b64 s[4:5], vcc
	s_xor_b64 s[14:15], exec, s[4:5]
	s_cbranch_execz .LBB0_80
	v_readlane_b32 s4, v245, 18
	s_waitcnt lgkmcnt(0)
	v_mov_b32_e32 v0, 0
	v_readlane_b32 s5, v245, 19
	s_nop 4
	global_load_dword v2, v0, s[4:5] sc1
	s_waitcnt vmcnt(0)
	v_cmp_eq_u32_e32 vcc, v2, v1
	s_and_saveexec_b64 s[18:19], vcc
	s_cbranch_execz .LBB0_79
	s_mov_b32 s4, 1
	s_mov_b64 s[20:21], 0
	s_branch .LBB0_70

; __device__ __forceinline__ unsigned xb_ld(unsigned* p)              { return __hip_atomic_load(p, __ATOMIC_RELAXED, __HIP_MEMORY_SCOPE_AGENT); }
; __device__ __forceinline__ unsigned xb_add(unsigned* p, unsigned v) { return __hip_atomic_fetch_add(p, v, __ATOMIC_RELAXED, __HIP_MEMORY_SCOPE_AGENT); }
; #define XB_SPIN(cond, bar) do { unsigned _sp = 0; while (cond) { __builtin_amdgcn_s_sleep(1); \
;     if ((++_sp & 255u) == 0u) { if (xb_ld(&(bar)[XB_TMO])) break; if (_sp > XB_SPIN_CAP) { atomicAdd(&(bar)[XB_TMO], 1u); break; } } } } while (0)
; __device__ __forceinline__ void xcd_barrier(const XcdBarrier& b) {
;     ...
;             const unsigned og = xb_add(&bar[XB_TOP], 1u);
;             const unsigned tg = og / nx;
;             if (og + 1u == (tg + 1u) * nx) xb_add(&bar[XB_TOPGEN], 1u);
;             else XB_SPIN(xb_ld(&bar[XB_TOPGEN]) == tg, bar);
.LBB0_83:
	s_or_b64 exec, exec, s[16:17]
	v_cvt_f32_u32_e32 v3, v0
	s_waitcnt vmcnt(0)
	v_readfirstlane_b32 s4, v2
	s_mov_b64 s[16:17], -1
	v_rcp_iflag_f32_e32 v3, v3
	v_add_u32_e32 v1, s4, v1
	v_add_u32_e32 v4, 1, v1
	v_readlane_b32 s4, v245, 22
	v_mul_f32_e32 v2, 0x4f7ffffe, v3
	v_cvt_u32_f32_e32 v2, v2
	v_sub_u32_e32 v3, 0, v0
	v_readlane_b32 s5, v245, 23
	v_mul_lo_u32 v3, v3, v2
	v_mul_hi_u32 v3, v2, v3
	v_add_u32_e32 v2, v2, v3
	v_mul_hi_u32 v2, v1, v2
	v_mul_lo_u32 v3, v2, v0
	v_sub_u32_e32 v1, v1, v3
	v_add_u32_e32 v5, 1, v2
	v_cmp_ge_u32_e32 vcc, v1, v0
	v_sub_u32_e32 v3, v1, v0
	s_nop 0
	v_cndmask_b32_e32 v2, v2, v5, vcc
	v_cndmask_b32_e32 v1, v1, v3, vcc
	v_add_u32_e32 v3, 1, v2
	v_cmp_ge_u32_e32 vcc, v1, v0
	s_nop 1
	v_cndmask_b32_e32 v2, v2, v3, vcc
	v_mul_lo_u32 v1, v0, v2
	v_add_u32_e32 v0, v1, v0
	v_cmp_ne_u32_e32 vcc, v4, v0
	s_mov_b64 s[98:99], vcc
	v_mov_b64_e32 v[0:1], s[4:5]
	s_and_saveexec_b64 s[14:15], vcc
	s_cbranch_execz .LBB0_95
	v_readlane_b32 s4, v245, 18
	v_mov_b32_e32 v0, 0
	v_readlane_b32 s5, v245, 19
	s_mov_b64 s[16:17], 0
	s_nop 3
	global_load_dword v1, v0, s[4:5] sc1
	s_waitcnt vmcnt(0)
	v_cmp_eq_u32_e32 vcc, v1, v250
	s_and_saveexec_b64 s[18:19], vcc
	s_cbranch_execz .LBB0_94
	s_mov_b32 s4, 1
	s_mov_b64 s[20:21], 0
	s_branch .LBB0_87

; __device__ __forceinline__ unsigned xb_ld(unsigned* p)              { return __hip_atomic_load(p, __ATOMIC_RELAXED, __HIP_MEMORY_SCOPE_AGENT); }
; __device__ __forceinline__ unsigned xb_add(unsigned* p, unsigned v) { return __hip_atomic_fetch_add(p, v, __ATOMIC_RELAXED, __HIP_MEMORY_SCOPE_AGENT); }
; #define XB_SPIN(cond, bar) do { unsigned _sp = 0; while (cond) { __builtin_amdgcn_s_sleep(1); \
;     if ((++_sp & 255u) == 0u) { if (xb_ld(&(bar)[XB_TMO])) break; if (_sp > XB_SPIN_CAP) { atomicAdd(&(bar)[XB_TMO], 1u); break; } } } } while (0)
; __device__ __forceinline__ void xcd_barrier(const XcdBarrier& b) {
;     ...
;             const unsigned og = xb_add(&bar[XB_TOP], 1u);
;             const unsigned tg = og / nx;
;             if (og + 1u == (tg + 1u) * nx) xb_add(&bar[XB_TOPGEN], 1u);
;             else XB_SPIN(xb_ld(&bar[XB_TOPGEN]) == tg, bar);
.LBB0_91:
	v_readlane_b32 s8, v245, 18
	v_readlane_b32 s9, v245, 19
	s_add_i32 s4, s4, 1
	s_mov_b64 s[24:25], -1
	s_nop 2
	global_load_dword v1, v0, s[8:9] sc1
	s_waitcnt vmcnt(0)
	v_cmp_ne_u32_e32 vcc, v1, v250
	s_orn2_b64 s[26:27], vcc, exec
	s_branch .LBB0_86

; __device__ __forceinline__ unsigned xb_ld(unsigned* p)              { return __hip_atomic_load(p, __ATOMIC_RELAXED, __HIP_MEMORY_SCOPE_AGENT); }
; __device__ __forceinline__ unsigned xb_add(unsigned* p, unsigned v) { return __hip_atomic_fetch_add(p, v, __ATOMIC_RELAXED, __HIP_MEMORY_SCOPE_AGENT); }
; #define XB_SPIN(cond, bar) do { unsigned _sp = 0; while (cond) { __builtin_amdgcn_s_sleep(1); \
;     if ((++_sp & 255u) == 0u) { if (xb_ld(&(bar)[XB_TMO])) break; if (_sp > XB_SPIN_CAP) { atomicAdd(&(bar)[XB_TMO], 1u); break; } } } } while (0)
; __device__ __forceinline__ void xcd_barrier(const XcdBarrier& b) {
;     ...
;             if (og + 1u == (tg + 1u) * nx) xb_add(&bar[XB_TOPGEN], 1u);
;             else XB_SPIN(xb_ld(&bar[XB_TOPGEN]) == tg, bar);
;             __builtin_amdgcn_fence(__ATOMIC_ACQUIRE, "agent");
;             xb_add(&bar[XB_XGEN(b.x)], 1u);
.LBB0_97:
	s_or_b64 exec, exec, s[14:15]
	s_mov_b64 s[14:15], exec
	v_mbcnt_lo_u32_b32 v0, s14, 0
	v_mbcnt_hi_u32_b32 v0, s15, v0
	v_cmp_eq_u32_e32 vcc, 0, v0
	s_waitcnt vmcnt(0)
	s_and_saveexec_b64 s[16:17], vcc
	s_cbranch_execz .LBB0_99
	s_bcnt1_i32_b64 s4, s[14:15]
	v_mov_b32_e32 v1, s4
	v_readlane_b32 s4, v245, 18
	v_mov_b32_e32 v0, 0
	v_readlane_b32 s5, v245, 19
	s_nop 4
	s_cmp_lg_u64 s[98:99], 0
	s_cbranch_scc1 .Lxb_norel_0
	v_mov_b32_e32 v251, 0x2400
	global_atomic_add v251, v1, s[94:95]
	global_atomic_add v251, v1, s[94:95] offset:256
	global_atomic_add v251, v1, s[94:95] offset:512
	global_atomic_add v251, v1, s[94:95] offset:768
	global_atomic_add v251, v1, s[94:95] offset:1024
	global_atomic_add v251, v1, s[94:95] offset:1280
	global_atomic_add v251, v1, s[94:95] offset:1536
	global_atomic_add v251, v1, s[94:95] offset:1792
	global_atomic_add v251, v1, s[94:95] offset:2048
	global_atomic_add v251, v1, s[94:95] offset:2304
	global_atomic_add v251, v1, s[94:95] offset:2560
	global_atomic_add v251, v1, s[94:95] offset:2816
	global_atomic_add v251, v1, s[94:95] offset:3072
	global_atomic_add v251, v1, s[94:95] offset:3328
	global_atomic_add v251, v1, s[94:95] offset:3584
	global_atomic_add v251, v1, s[94:95] offset:3840
.Lxb_norel_0:
.LBB0_99:
	s_or_b64 exec, exec, s[16:17]
	s_waitcnt vmcnt(0)

; __device__ __forceinline__ unsigned xb_ld(unsigned* p)              { return __hip_atomic_load(p, __ATOMIC_RELAXED, __HIP_MEMORY_SCOPE_AGENT); }
; __device__ __forceinline__ unsigned xb_add(unsigned* p, unsigned v) { return __hip_atomic_fetch_add(p, v, __ATOMIC_RELAXED, __HIP_MEMORY_SCOPE_AGENT); }
; #define XB_SPIN(cond, bar) do { unsigned _sp = 0; while (cond) { __builtin_amdgcn_s_sleep(1); \
;     if ((++_sp & 255u) == 0u) { if (xb_ld(&(bar)[XB_TMO])) break; if (_sp > XB_SPIN_CAP) { atomicAdd(&(bar)[XB_TMO], 1u); break; } } } } while (0)
; __device__ __forceinline__ void xcd_barrier(const XcdBarrier& b) {
;     ...
;         unsigned nloc = b.st[0], nx = b.st[1];
;         if (nloc == 0u) { xcd_barrier_complete(bar, b.x, nloc, nx); b.st[0] = nloc; b.st[1] = nx; }
;         const unsigned old = xb_add(&bar[XB_XSUB(b.x)], 1u);
;         const unsigned gen = old / nloc;
;         if (old + 1u == (gen + 1u) * nloc) {
;             __builtin_amdgcn_fence(__ATOMIC_RELEASE, "agent");
;             asm volatile("s_waitcnt vmcnt(0)" ::: "memory");
;             const unsigned og = xb_add(&bar[XB_TOP], 1u);
;             const unsigned tg = og / nx;
;             if (og + 1u == (tg + 1u) * nx) xb_add(&bar[XB_TOPGEN], 1u);
;             else XB_SPIN(xb_ld(&bar[XB_TOPGEN]) == tg, bar);
;             __builtin_amdgcn_fence(__ATOMIC_ACQUIRE, "agent");
;             xb_add(&bar[XB_XGEN(b.x)], 1u);
;             asm volatile("s_waitcnt vmcnt(0)" ::: "memory");
;         } else {
;             XB_SPIN(xb_ld(&bar[XB_XGEN(b.x)]) == gen, bar);
.LBB0_139:
	s_or_b64 exec, exec, s[8:9]
	buffer_inv sc1
	v_cvt_f32_u32_e32 v4, v2
	s_waitcnt vmcnt(1)
	v_readfirstlane_b32 s3, v3
	v_sub_u32_e32 v3, 0, v2
	v_rcp_iflag_f32_e32 v4, v4
	v_add_u32_e32 v5, s3, v1
	v_mul_f32_e32 v4, 0x4f7ffffe, v4
	v_cvt_u32_f32_e32 v4, v4
	v_mul_lo_u32 v1, v3, v4
	v_mul_hi_u32 v1, v4, v1
	v_add_u32_e32 v1, v4, v1
	v_mul_hi_u32 v1, v5, v1
	v_mul_lo_u32 v3, v1, v2
	v_sub_u32_e32 v3, v5, v3
	v_add_u32_e32 v4, 1, v1
	v_cmp_ge_u32_e32 vcc, v3, v2
	s_nop 1
	v_cndmask_b32_e32 v1, v1, v4, vcc
	v_sub_u32_e32 v4, v3, v2
	v_cndmask_b32_e32 v3, v3, v4, vcc
	v_add_u32_e32 v4, 1, v1
	v_cmp_ge_u32_e32 vcc, v3, v2
	v_add_u32_e32 v3, 1, v5
	s_nop 0
	v_cndmask_b32_e32 v1, v1, v4, vcc
	v_mul_lo_u32 v4, v2, v1
	v_add_u32_e32 v2, v4, v2
	v_cmp_ne_u32_e32 vcc, v3, v2
	v_mov_b32_e32 v250, v1
	s_and_saveexec_b64 s[4:5], vcc
	s_xor_b64 s[8:9], exec, s[4:5]
	s_cbranch_execz .LBB0_153
	v_readlane_b32 s4, v245, 18
	s_waitcnt lgkmcnt(0)
	v_mov_b32_e32 v0, 0
	v_readlane_b32 s5, v245, 19
	s_nop 4
	global_load_dword v2, v0, s[4:5] sc1
	s_waitcnt vmcnt(0)
	v_cmp_eq_u32_e32 vcc, v2, v1
	s_and_saveexec_b64 s[14:15], vcc
	s_cbranch_execz .LBB0_152
	s_mov_b32 s3, 1
	s_mov_b64 s[18:19], 0
	s_branch .LBB0_143

; __device__ __forceinline__ unsigned xb_ld(unsigned* p)              { return __hip_atomic_load(p, __ATOMIC_RELAXED, __HIP_MEMORY_SCOPE_AGENT); }
; __device__ __forceinline__ unsigned xb_add(unsigned* p, unsigned v) { return __hip_atomic_fetch_add(p, v, __ATOMIC_RELAXED, __HIP_MEMORY_SCOPE_AGENT); }
; #define XB_SPIN(cond, bar) do { unsigned _sp = 0; while (cond) { __builtin_amdgcn_s_sleep(1); \
;     if ((++_sp & 255u) == 0u) { if (xb_ld(&(bar)[XB_TMO])) break; if (_sp > XB_SPIN_CAP) { atomicAdd(&(bar)[XB_TMO], 1u); break; } } } } while (0)
; __device__ __forceinline__ void xcd_barrier(const XcdBarrier& b) {
;     ...
;             const unsigned og = xb_add(&bar[XB_TOP], 1u);
;             const unsigned tg = og / nx;
;             if (og + 1u == (tg + 1u) * nx) xb_add(&bar[XB_TOPGEN], 1u);
;             else XB_SPIN(xb_ld(&bar[XB_TOPGEN]) == tg, bar);
.LBB0_156:
	s_or_b64 exec, exec, s[14:15]
	v_cvt_f32_u32_e32 v3, v0
	s_waitcnt vmcnt(0)
	v_readfirstlane_b32 s3, v2
	v_readlane_b32 s4, v245, 22
	v_readlane_b32 s5, v245, 23
	v_rcp_iflag_f32_e32 v3, v3
	v_add_u32_e32 v1, s3, v1
	v_add_u32_e32 v4, 1, v1
	s_mov_b64 s[14:15], -1
	v_mul_f32_e32 v2, 0x4f7ffffe, v3
	v_cvt_u32_f32_e32 v2, v2
	v_sub_u32_e32 v3, 0, v0
	v_mul_lo_u32 v3, v3, v2
	v_mul_hi_u32 v3, v2, v3
	v_add_u32_e32 v2, v2, v3
	v_mul_hi_u32 v2, v1, v2
	v_mul_lo_u32 v3, v2, v0
	v_sub_u32_e32 v1, v1, v3
	v_add_u32_e32 v5, 1, v2
	v_cmp_ge_u32_e32 vcc, v1, v0
	v_sub_u32_e32 v3, v1, v0
	s_nop 0
	v_cndmask_b32_e32 v2, v2, v5, vcc
	v_cndmask_b32_e32 v1, v1, v3, vcc
	v_add_u32_e32 v3, 1, v2
	v_cmp_ge_u32_e32 vcc, v1, v0
	s_nop 1
	v_cndmask_b32_e32 v2, v2, v3, vcc
	v_mul_lo_u32 v1, v0, v2
	v_add_u32_e32 v0, v1, v0
	v_cmp_ne_u32_e32 vcc, v4, v0
	s_mov_b64 s[98:99], vcc
	v_mov_b64_e32 v[0:1], s[4:5]
	s_and_saveexec_b64 s[8:9], vcc
	s_cbranch_execz .LBB0_168
	v_readlane_b32 s4, v245, 18
	v_mov_b32_e32 v0, 0
	v_readlane_b32 s5, v245, 19
	s_mov_b64 s[16:17], 0
	s_nop 3
	global_load_dword v1, v0, s[4:5] sc1
	s_waitcnt vmcnt(0)
	v_cmp_eq_u32_e32 vcc, v1, v250
	s_and_saveexec_b64 s[14:15], vcc
	s_cbranch_execz .LBB0_167
	s_mov_b32 s3, 1
	s_mov_b64 s[18:19], 0
	s_branch .LBB0_160

; __device__ __forceinline__ unsigned xb_ld(unsigned* p)              { return __hip_atomic_load(p, __ATOMIC_RELAXED, __HIP_MEMORY_SCOPE_AGENT); }
; __device__ __forceinline__ unsigned xb_add(unsigned* p, unsigned v) { return __hip_atomic_fetch_add(p, v, __ATOMIC_RELAXED, __HIP_MEMORY_SCOPE_AGENT); }
; #define XB_SPIN(cond, bar) do { unsigned _sp = 0; while (cond) { __builtin_amdgcn_s_sleep(1); \
;     if ((++_sp & 255u) == 0u) { if (xb_ld(&(bar)[XB_TMO])) break; if (_sp > XB_SPIN_CAP) { atomicAdd(&(bar)[XB_TMO], 1u); break; } } } } while (0)
; __device__ __forceinline__ void xcd_barrier(const XcdBarrier& b) {
;     ...
;             const unsigned og = xb_add(&bar[XB_TOP], 1u);
;             const unsigned tg = og / nx;
;             if (og + 1u == (tg + 1u) * nx) xb_add(&bar[XB_TOPGEN], 1u);
;             else XB_SPIN(xb_ld(&bar[XB_TOPGEN]) == tg, bar);
.LBB0_164:
	v_readlane_b32 s4, v245, 18
	v_readlane_b32 s5, v245, 19
	s_add_i32 s3, s3, 1
	s_mov_b64 s[22:23], -1
	s_nop 2
	global_load_dword v1, v0, s[4:5] sc1
	s_waitcnt vmcnt(0)
	v_cmp_ne_u32_e32 vcc, v1, v250
	s_orn2_b64 s[24:25], vcc, exec
	s_branch .LBB0_159

; __device__ __forceinline__ unsigned xb_ld(unsigned* p)              { return __hip_atomic_load(p, __ATOMIC_RELAXED, __HIP_MEMORY_SCOPE_AGENT); }
; __device__ __forceinline__ unsigned xb_add(unsigned* p, unsigned v) { return __hip_atomic_fetch_add(p, v, __ATOMIC_RELAXED, __HIP_MEMORY_SCOPE_AGENT); }
; #define XB_SPIN(cond, bar) do { unsigned _sp = 0; while (cond) { __builtin_amdgcn_s_sleep(1); \
;     if ((++_sp & 255u) == 0u) { if (xb_ld(&(bar)[XB_TMO])) break; if (_sp > XB_SPIN_CAP) { atomicAdd(&(bar)[XB_TMO], 1u); break; } } } } while (0)
; __device__ __forceinline__ void xcd_barrier(const XcdBarrier& b) {
;     ...
;             if (og + 1u == (tg + 1u) * nx) xb_add(&bar[XB_TOPGEN], 1u);
;             else XB_SPIN(xb_ld(&bar[XB_TOPGEN]) == tg, bar);
;             __builtin_amdgcn_fence(__ATOMIC_ACQUIRE, "agent");
;             xb_add(&bar[XB_XGEN(b.x)], 1u);
.LBB0_170:
	s_or_b64 exec, exec, s[8:9]
	s_mov_b64 s[8:9], exec
	v_mbcnt_lo_u32_b32 v0, s8, 0
	v_mbcnt_hi_u32_b32 v0, s9, v0
	v_cmp_eq_u32_e32 vcc, 0, v0
	s_waitcnt vmcnt(0)
	s_and_saveexec_b64 s[14:15], vcc
	s_cbranch_execz .LBB0_172
	s_bcnt1_i32_b64 s3, s[8:9]
	v_readlane_b32 s4, v245, 18
	v_mov_b32_e32 v0, 0
	v_mov_b32_e32 v1, s3
	v_readlane_b32 s5, v245, 19
	s_nop 4
	s_cmp_lg_u64 s[98:99], 0
	s_cbranch_scc1 .Lxb_norel_1
	v_mov_b32_e32 v251, 0x2400
	global_atomic_add v251, v1, s[94:95]
	global_atomic_add v251, v1, s[94:95] offset:256
	global_atomic_add v251, v1, s[94:95] offset:512
	global_atomic_add v251, v1, s[94:95] offset:768
	global_atomic_add v251, v1, s[94:95] offset:1024
	global_atomic_add v251, v1, s[94:95] offset:1280
	global_atomic_add v251, v1, s[94:95] offset:1536
	global_atomic_add v251, v1, s[94:95] offset:1792
	global_atomic_add v251, v1, s[94:95] offset:2048
	global_atomic_add v251, v1, s[94:95] offset:2304
	global_atomic_add v251, v1, s[94:95] offset:2560
	global_atomic_add v251, v1, s[94:95] offset:2816
	global_atomic_add v251, v1, s[94:95] offset:3072
	global_atomic_add v251, v1, s[94:95] offset:3328
	global_atomic_add v251, v1, s[94:95] offset:3584
	global_atomic_add v251, v1, s[94:95] offset:3840
.Lxb_norel_1:
.LBB0_172:
	s_or_b64 exec, exec, s[14:15]
	s_waitcnt vmcnt(0)

; __device__ __forceinline__ unsigned xb_ld(unsigned* p)              { return __hip_atomic_load(p, __ATOMIC_RELAXED, __HIP_MEMORY_SCOPE_AGENT); }
; __device__ __forceinline__ unsigned xb_add(unsigned* p, unsigned v) { return __hip_atomic_fetch_add(p, v, __ATOMIC_RELAXED, __HIP_MEMORY_SCOPE_AGENT); }
; #define XB_SPIN(cond, bar) do { unsigned _sp = 0; while (cond) { __builtin_amdgcn_s_sleep(1); \
;     if ((++_sp & 255u) == 0u) { if (xb_ld(&(bar)[XB_TMO])) break; if (_sp > XB_SPIN_CAP) { atomicAdd(&(bar)[XB_TMO], 1u); break; } } } } while (0)
; __device__ __forceinline__ void xcd_barrier(const XcdBarrier& b) {
;     ...
;         unsigned nloc = b.st[0], nx = b.st[1];
;         if (nloc == 0u) { xcd_barrier_complete(bar, b.x, nloc, nx); b.st[0] = nloc; b.st[1] = nx; }
;         const unsigned old = xb_add(&bar[XB_XSUB(b.x)], 1u);
;         const unsigned gen = old / nloc;
;         if (old + 1u == (gen + 1u) * nloc) {
;             __builtin_amdgcn_fence(__ATOMIC_RELEASE, "agent");
;             asm volatile("s_waitcnt vmcnt(0)" ::: "memory");
;             const unsigned og = xb_add(&bar[XB_TOP], 1u);
;             const unsigned tg = og / nx;
;             if (og + 1u == (tg + 1u) * nx) xb_add(&bar[XB_TOPGEN], 1u);
;             else XB_SPIN(xb_ld(&bar[XB_TOPGEN]) == tg, bar);
;             __builtin_amdgcn_fence(__ATOMIC_ACQUIRE, "agent");
;             xb_add(&bar[XB_XGEN(b.x)], 1u);
;             asm volatile("s_waitcnt vmcnt(0)" ::: "memory");
;         } else {
;             XB_SPIN(xb_ld(&bar[XB_XGEN(b.x)]) == gen, bar);
.LBB0_227:
	s_or_b64 exec, exec, s[16:17]
	buffer_inv sc1
	v_cvt_f32_u32_e32 v5, v3
	s_waitcnt vmcnt(1)
	v_readfirstlane_b32 s16, v4
	v_sub_u32_e32 v4, 0, v3
	v_rcp_iflag_f32_e32 v5, v5
	v_add_u32_e32 v6, s16, v0
	v_mul_f32_e32 v5, 0x4f7ffffe, v5
	v_cvt_u32_f32_e32 v5, v5
	v_mul_lo_u32 v0, v4, v5
	v_mul_hi_u32 v0, v5, v0
	v_add_u32_e32 v0, v5, v0
	v_mul_hi_u32 v0, v6, v0
	v_mul_lo_u32 v4, v0, v3
	v_sub_u32_e32 v4, v6, v4
	v_add_u32_e32 v5, 1, v0
	v_cmp_ge_u32_e32 vcc, v4, v3
	s_nop 1
	v_cndmask_b32_e32 v0, v0, v5, vcc
	v_sub_u32_e32 v5, v4, v3
	v_cndmask_b32_e32 v4, v4, v5, vcc
	v_add_u32_e32 v5, 1, v0
	v_cmp_ge_u32_e32 vcc, v4, v3
	v_add_u32_e32 v4, 1, v6
	s_nop 0
	v_cndmask_b32_e32 v0, v0, v5, vcc
	v_mul_lo_u32 v5, v3, v0
	v_add_u32_e32 v3, v5, v3
	v_cmp_ne_u32_e32 vcc, v4, v3
	v_mov_b32_e32 v250, v0
	s_and_saveexec_b64 s[16:17], vcc
	s_xor_b64 s[20:21], exec, s[16:17]
	s_cbranch_execz .LBB0_241
	v_readlane_b32 s16, v245, 18
	v_readlane_b32 s17, v245, 19
	s_waitcnt lgkmcnt(0)
	s_nop 3
	global_load_dword v2, v1, s[16:17] sc1
	s_waitcnt vmcnt(0)
	v_cmp_eq_u32_e32 vcc, v2, v0
	s_and_saveexec_b64 s[22:23], vcc
	s_cbranch_execz .LBB0_240
	s_mov_b32 s44, 1
	s_mov_b64 s[36:37], 0
	s_branch .LBB0_231

; __device__ __forceinline__ unsigned xb_ld(unsigned* p)              { return __hip_atomic_load(p, __ATOMIC_RELAXED, __HIP_MEMORY_SCOPE_AGENT); }
; __device__ __forceinline__ unsigned xb_add(unsigned* p, unsigned v) { return __hip_atomic_fetch_add(p, v, __ATOMIC_RELAXED, __HIP_MEMORY_SCOPE_AGENT); }
; #define XB_SPIN(cond, bar) do { unsigned _sp = 0; while (cond) { __builtin_amdgcn_s_sleep(1); \
;     if ((++_sp & 255u) == 0u) { if (xb_ld(&(bar)[XB_TMO])) break; if (_sp > XB_SPIN_CAP) { atomicAdd(&(bar)[XB_TMO], 1u); break; } } } } while (0)
; __device__ __forceinline__ void xcd_barrier(const XcdBarrier& b) {
;     ...
;             const unsigned og = xb_add(&bar[XB_TOP], 1u);
;             const unsigned tg = og / nx;
;             if (og + 1u == (tg + 1u) * nx) xb_add(&bar[XB_TOPGEN], 1u);
;             else XB_SPIN(xb_ld(&bar[XB_TOPGEN]) == tg, bar);
.LBB0_244:
	s_or_b64 exec, exec, s[20:21]
	s_waitcnt vmcnt(0)
	v_readfirstlane_b32 s16, v3
	v_sub_u32_e32 v4, 0, v2
	s_mov_b64 s[22:23], -1
	v_add_u32_e32 v3, s16, v0
	v_cvt_f32_u32_e32 v0, v2
	v_readlane_b32 s16, v245, 22
	v_readlane_b32 s17, v245, 23
	v_rcp_iflag_f32_e32 v0, v0
	s_nop 0
	v_mul_f32_e32 v0, 0x4f7ffffe, v0
	v_cvt_u32_f32_e32 v0, v0
	v_mul_lo_u32 v4, v4, v0
	v_mul_hi_u32 v4, v0, v4
	v_add_u32_e32 v0, v0, v4
	v_mul_hi_u32 v0, v3, v0
	v_mul_lo_u32 v4, v0, v2
	v_sub_u32_e32 v4, v3, v4
	v_cmp_ge_u32_e32 vcc, v4, v2
	v_add_u32_e32 v5, 1, v0
	v_add_u32_e32 v3, 1, v3
	v_cndmask_b32_e32 v0, v0, v5, vcc
	v_sub_u32_e32 v5, v4, v2
	v_cndmask_b32_e32 v4, v4, v5, vcc
	v_cmp_ge_u32_e32 vcc, v4, v2
	v_add_u32_e32 v4, 1, v0
	s_nop 0
	v_cndmask_b32_e32 v0, v0, v4, vcc
	v_mul_lo_u32 v4, v2, v0
	v_add_u32_e32 v2, v4, v2
	v_cmp_ne_u32_e32 vcc, v3, v2
	s_mov_b64 s[98:99], vcc
	v_mov_b64_e32 v[2:3], s[16:17]
	s_and_saveexec_b64 s[20:21], vcc
	s_cbranch_execz .LBB0_256
	v_readlane_b32 s16, v245, 18
	v_readlane_b32 s17, v245, 19
	s_nop 4
	global_load_dword v2, v1, s[16:17] sc1
	s_mov_b64 s[16:17], 0
	s_waitcnt vmcnt(0)
	v_cmp_eq_u32_e32 vcc, v2, v250
	s_and_saveexec_b64 s[22:23], vcc
	s_cbranch_execz .LBB0_255
	s_mov_b32 s44, 1
	s_mov_b64 s[36:37], 0
	s_branch .LBB0_248

; __device__ __forceinline__ unsigned xb_ld(unsigned* p)              { return __hip_atomic_load(p, __ATOMIC_RELAXED, __HIP_MEMORY_SCOPE_AGENT); }
; __device__ __forceinline__ unsigned xb_add(unsigned* p, unsigned v) { return __hip_atomic_fetch_add(p, v, __ATOMIC_RELAXED, __HIP_MEMORY_SCOPE_AGENT); }
; #define XB_SPIN(cond, bar) do { unsigned _sp = 0; while (cond) { __builtin_amdgcn_s_sleep(1); \
;     if ((++_sp & 255u) == 0u) { if (xb_ld(&(bar)[XB_TMO])) break; if (_sp > XB_SPIN_CAP) { atomicAdd(&(bar)[XB_TMO], 1u); break; } } } } while (0)
; __device__ __forceinline__ void xcd_barrier(const XcdBarrier& b) {
;     ...
;             const unsigned og = xb_add(&bar[XB_TOP], 1u);
;             const unsigned tg = og / nx;
;             if (og + 1u == (tg + 1u) * nx) xb_add(&bar[XB_TOPGEN], 1u);
;             else XB_SPIN(xb_ld(&bar[XB_TOPGEN]) == tg, bar);
.LBB0_252:
	v_readlane_b32 s16, v245, 18
	v_readlane_b32 s17, v245, 19
	s_add_i32 s44, s44, 1
	s_mov_b64 s[42:43], -1
	s_nop 2
	global_load_dword v2, v1, s[16:17] sc1
	s_waitcnt vmcnt(0)
	v_cmp_ne_u32_e32 vcc, v2, v250
	s_orn2_b64 s[40:41], vcc, exec
	s_branch .LBB0_247

; __device__ __forceinline__ unsigned xb_ld(unsigned* p)              { return __hip_atomic_load(p, __ATOMIC_RELAXED, __HIP_MEMORY_SCOPE_AGENT); }
; __device__ __forceinline__ unsigned xb_add(unsigned* p, unsigned v) { return __hip_atomic_fetch_add(p, v, __ATOMIC_RELAXED, __HIP_MEMORY_SCOPE_AGENT); }
; #define XB_SPIN(cond, bar) do { unsigned _sp = 0; while (cond) { __builtin_amdgcn_s_sleep(1); \
;     if ((++_sp & 255u) == 0u) { if (xb_ld(&(bar)[XB_TMO])) break; if (_sp > XB_SPIN_CAP) { atomicAdd(&(bar)[XB_TMO], 1u); break; } } } } while (0)
; __device__ __forceinline__ void xcd_barrier(const XcdBarrier& b) {
;     ...
;             if (og + 1u == (tg + 1u) * nx) xb_add(&bar[XB_TOPGEN], 1u);
;             else XB_SPIN(xb_ld(&bar[XB_TOPGEN]) == tg, bar);
;             __builtin_amdgcn_fence(__ATOMIC_ACQUIRE, "agent");
;             xb_add(&bar[XB_XGEN(b.x)], 1u);
.LBB0_258:
	s_or_b64 exec, exec, s[16:17]
	s_mov_b64 s[16:17], exec
	v_mbcnt_lo_u32_b32 v0, s16, 0
	v_mbcnt_hi_u32_b32 v0, s17, v0
	v_cmp_eq_u32_e32 vcc, 0, v0
	s_waitcnt vmcnt(0)
	s_and_saveexec_b64 s[20:21], vcc
	s_cbranch_execz .LBB0_260
	s_bcnt1_i32_b64 s16, s[16:17]
	v_mov_b32_e32 v0, s16
	v_readlane_b32 s16, v245, 18
	v_readlane_b32 s17, v245, 19
	s_nop 4
	s_cmp_lg_u64 s[98:99], 0
	s_cbranch_scc1 .Lxb_norel_2
	v_mov_b32_e32 v251, 0x2400
	global_atomic_add v251, v0, s[94:95]
	global_atomic_add v251, v0, s[94:95] offset:256
	global_atomic_add v251, v0, s[94:95] offset:512
	global_atomic_add v251, v0, s[94:95] offset:768
	global_atomic_add v251, v0, s[94:95] offset:1024
	global_atomic_add v251, v0, s[94:95] offset:1280
	global_atomic_add v251, v0, s[94:95] offset:1536
	global_atomic_add v251, v0, s[94:95] offset:1792
	global_atomic_add v251, v0, s[94:95] offset:2048
	global_atomic_add v251, v0, s[94:95] offset:2304
	global_atomic_add v251, v0, s[94:95] offset:2560
	global_atomic_add v251, v0, s[94:95] offset:2816
	global_atomic_add v251, v0, s[94:95] offset:3072
	global_atomic_add v251, v0, s[94:95] offset:3328
	global_atomic_add v251, v0, s[94:95] offset:3584
	global_atomic_add v251, v0, s[94:95] offset:3840
.Lxb_norel_2:
.LBB0_260:
	s_or_b64 exec, exec, s[20:21]
	s_waitcnt vmcnt(0)

; __device__ __forceinline__ unsigned xb_ld(unsigned* p)              { return __hip_atomic_load(p, __ATOMIC_RELAXED, __HIP_MEMORY_SCOPE_AGENT); }
; __device__ __forceinline__ unsigned xb_add(unsigned* p, unsigned v) { return __hip_atomic_fetch_add(p, v, __ATOMIC_RELAXED, __HIP_MEMORY_SCOPE_AGENT); }
; #define XB_SPIN(cond, bar) do { unsigned _sp = 0; while (cond) { __builtin_amdgcn_s_sleep(1); \
;     if ((++_sp & 255u) == 0u) { if (xb_ld(&(bar)[XB_TMO])) break; if (_sp > XB_SPIN_CAP) { atomicAdd(&(bar)[XB_TMO], 1u); break; } } } } while (0)
; __device__ __forceinline__ void xcd_barrier(const XcdBarrier& b) {
;     ...
;         unsigned nloc = b.st[0], nx = b.st[1];
;         if (nloc == 0u) { xcd_barrier_complete(bar, b.x, nloc, nx); b.st[0] = nloc; b.st[1] = nx; }
;         const unsigned old = xb_add(&bar[XB_XSUB(b.x)], 1u);
;         const unsigned gen = old / nloc;
;         if (old + 1u == (gen + 1u) * nloc) {
;             __builtin_amdgcn_fence(__ATOMIC_RELEASE, "agent");
;             asm volatile("s_waitcnt vmcnt(0)" ::: "memory");
;             const unsigned og = xb_add(&bar[XB_TOP], 1u);
;             const unsigned tg = og / nx;
;             if (og + 1u == (tg + 1u) * nx) xb_add(&bar[XB_TOPGEN], 1u);
;             else XB_SPIN(xb_ld(&bar[XB_TOPGEN]) == tg, bar);
;             __builtin_amdgcn_fence(__ATOMIC_ACQUIRE, "agent");
;             xb_add(&bar[XB_XGEN(b.x)], 1u);
;             asm volatile("s_waitcnt vmcnt(0)" ::: "memory");
;         } else {
;             XB_SPIN(xb_ld(&bar[XB_XGEN(b.x)]) == gen, bar);
.LBB0_396:
	s_or_b64 exec, exec, s[16:17]
	buffer_inv sc1
	v_cvt_f32_u32_e32 v5, v3
	s_waitcnt vmcnt(1)
	v_readfirstlane_b32 s16, v4
	v_sub_u32_e32 v4, 0, v3
	v_rcp_iflag_f32_e32 v5, v5
	v_add_u32_e32 v6, s16, v0
	v_mul_f32_e32 v5, 0x4f7ffffe, v5
	v_cvt_u32_f32_e32 v5, v5
	v_mul_lo_u32 v0, v4, v5
	v_mul_hi_u32 v0, v5, v0
	v_add_u32_e32 v0, v5, v0
	v_mul_hi_u32 v0, v6, v0
	v_mul_lo_u32 v4, v0, v3
	v_sub_u32_e32 v4, v6, v4
	v_add_u32_e32 v5, 1, v0
	v_cmp_ge_u32_e32 vcc, v4, v3
	s_nop 1
	v_cndmask_b32_e32 v0, v0, v5, vcc
	v_sub_u32_e32 v5, v4, v3
	v_cndmask_b32_e32 v4, v4, v5, vcc
	v_add_u32_e32 v5, 1, v0
	v_cmp_ge_u32_e32 vcc, v4, v3
	v_add_u32_e32 v4, 1, v6
	s_nop 0
	v_cndmask_b32_e32 v0, v0, v5, vcc
	v_mul_lo_u32 v5, v3, v0
	v_add_u32_e32 v3, v5, v3
	v_cmp_ne_u32_e32 vcc, v4, v3
	v_mov_b32_e32 v250, v0
	s_and_saveexec_b64 s[16:17], vcc
	s_xor_b64 s[36:37], exec, s[16:17]
	s_cbranch_execz .LBB0_410
	v_readlane_b32 s16, v245, 18
	v_readlane_b32 s17, v245, 19
	s_waitcnt lgkmcnt(0)
	s_nop 3
	global_load_dword v2, v1, s[16:17] sc1
	s_waitcnt vmcnt(0)
	v_cmp_eq_u32_e32 vcc, v2, v0
	s_and_saveexec_b64 s[38:39], vcc
	s_cbranch_execz .LBB0_409
	s_mov_b32 s23, 1
	s_mov_b64 s[40:41], 0
	s_branch .LBB0_400

; __device__ __forceinline__ unsigned xb_ld(unsigned* p)              { return __hip_atomic_load(p, __ATOMIC_RELAXED, __HIP_MEMORY_SCOPE_AGENT); }
; __device__ __forceinline__ unsigned xb_add(unsigned* p, unsigned v) { return __hip_atomic_fetch_add(p, v, __ATOMIC_RELAXED, __HIP_MEMORY_SCOPE_AGENT); }
; #define XB_SPIN(cond, bar) do { unsigned _sp = 0; while (cond) { __builtin_amdgcn_s_sleep(1); \
;     if ((++_sp & 255u) == 0u) { if (xb_ld(&(bar)[XB_TMO])) break; if (_sp > XB_SPIN_CAP) { atomicAdd(&(bar)[XB_TMO], 1u); break; } } } } while (0)
; __device__ __forceinline__ void xcd_barrier(const XcdBarrier& b) {
;     ...
;             const unsigned og = xb_add(&bar[XB_TOP], 1u);
;             const unsigned tg = og / nx;
;             if (og + 1u == (tg + 1u) * nx) xb_add(&bar[XB_TOPGEN], 1u);
;             else XB_SPIN(xb_ld(&bar[XB_TOPGEN]) == tg, bar);
.LBB0_413:
	s_or_b64 exec, exec, s[36:37]
	s_waitcnt vmcnt(0)
	v_readfirstlane_b32 s16, v3
	v_sub_u32_e32 v4, 0, v2
	s_mov_b64 s[38:39], -1
	v_add_u32_e32 v3, s16, v0
	v_cvt_f32_u32_e32 v0, v2
	v_readlane_b32 s16, v245, 22
	v_readlane_b32 s17, v245, 23
	v_rcp_iflag_f32_e32 v0, v0
	s_nop 0
	v_mul_f32_e32 v0, 0x4f7ffffe, v0
	v_cvt_u32_f32_e32 v0, v0
	v_mul_lo_u32 v4, v4, v0
	v_mul_hi_u32 v4, v0, v4
	v_add_u32_e32 v0, v0, v4
	v_mul_hi_u32 v0, v3, v0
	v_mul_lo_u32 v4, v0, v2
	v_sub_u32_e32 v4, v3, v4
	v_cmp_ge_u32_e32 vcc, v4, v2
	v_add_u32_e32 v5, 1, v0
	v_add_u32_e32 v3, 1, v3
	v_cndmask_b32_e32 v0, v0, v5, vcc
	v_sub_u32_e32 v5, v4, v2
	v_cndmask_b32_e32 v4, v4, v5, vcc
	v_cmp_ge_u32_e32 vcc, v4, v2
	v_add_u32_e32 v4, 1, v0
	s_nop 0
	v_cndmask_b32_e32 v0, v0, v4, vcc
	v_mul_lo_u32 v4, v2, v0
	v_add_u32_e32 v2, v4, v2
	v_cmp_ne_u32_e32 vcc, v3, v2
	s_mov_b64 s[98:99], vcc
	v_mov_b64_e32 v[2:3], s[16:17]
	s_and_saveexec_b64 s[36:37], vcc
	s_cbranch_execz .LBB0_425
	v_readlane_b32 s16, v245, 18
	v_readlane_b32 s17, v245, 19
	s_nop 4
	global_load_dword v2, v1, s[16:17] sc1
	s_mov_b64 s[16:17], 0
	s_waitcnt vmcnt(0)
	v_cmp_eq_u32_e32 vcc, v2, v250
	s_and_saveexec_b64 s[38:39], vcc
	s_cbranch_execz .LBB0_424
	s_mov_b32 s23, 1
	s_mov_b64 s[40:41], 0
	s_branch .LBB0_417

; __device__ __forceinline__ unsigned xb_ld(unsigned* p)              { return __hip_atomic_load(p, __ATOMIC_RELAXED, __HIP_MEMORY_SCOPE_AGENT); }
; #define XB_SPIN(cond, bar) do { unsigned _sp = 0; while (cond) { __builtin_amdgcn_s_sleep(1); \
;     if ((++_sp & 255u) == 0u) { if (xb_ld(&(bar)[XB_TMO])) break; if (_sp > XB_SPIN_CAP) { atomicAdd(&(bar)[XB_TMO], 1u); break; } } } } while (0)
; __device__ __forceinline__ void xcd_barrier(const XcdBarrier& b) {
;     ...
;             else XB_SPIN(xb_ld(&bar[XB_TOPGEN]) == tg, bar);
.LBB0_421:
	v_readlane_b32 s16, v245, 18
	v_readlane_b32 s17, v245, 19
	s_add_i32 s23, s23, 1
	s_mov_b64 s[46:47], -1
	s_nop 2
	global_load_dword v2, v1, s[16:17] sc1
	s_waitcnt vmcnt(0)
	v_cmp_ne_u32_e32 vcc, v2, v250
	s_orn2_b64 s[44:45], vcc, exec
	s_branch .LBB0_416

; __device__ __forceinline__ unsigned xb_ld(unsigned* p)              { return __hip_atomic_load(p, __ATOMIC_RELAXED, __HIP_MEMORY_SCOPE_AGENT); }
; __device__ __forceinline__ unsigned xb_add(unsigned* p, unsigned v) { return __hip_atomic_fetch_add(p, v, __ATOMIC_RELAXED, __HIP_MEMORY_SCOPE_AGENT); }
; #define XB_SPIN(cond, bar) do { unsigned _sp = 0; while (cond) { __builtin_amdgcn_s_sleep(1); \
;     if ((++_sp & 255u) == 0u) { if (xb_ld(&(bar)[XB_TMO])) break; if (_sp > XB_SPIN_CAP) { atomicAdd(&(bar)[XB_TMO], 1u); break; } } } } while (0)
; __device__ __forceinline__ void xcd_barrier(const XcdBarrier& b) {
;     ...
;             if (og + 1u == (tg + 1u) * nx) xb_add(&bar[XB_TOPGEN], 1u);
;             else XB_SPIN(xb_ld(&bar[XB_TOPGEN]) == tg, bar);
;             __builtin_amdgcn_fence(__ATOMIC_ACQUIRE, "agent");
;             xb_add(&bar[XB_XGEN(b.x)], 1u);
;             asm volatile("s_waitcnt vmcnt(0)" ::: "memory");
.LBB0_427:
	s_or_b64 exec, exec, s[16:17]
	s_mov_b64 s[16:17], exec
	v_mbcnt_lo_u32_b32 v0, s16, 0
	v_mbcnt_hi_u32_b32 v0, s17, v0
	v_cmp_eq_u32_e32 vcc, 0, v0
	s_waitcnt vmcnt(0)
	s_and_saveexec_b64 s[36:37], vcc
	s_cbranch_execz .LBB0_429
	s_bcnt1_i32_b64 s16, s[16:17]
	v_mov_b32_e32 v0, s16
	v_readlane_b32 s16, v245, 18
	v_readlane_b32 s17, v245, 19
	s_nop 4
	s_cmp_lg_u64 s[98:99], 0
	s_cbranch_scc1 .Lxb_norel_3
	v_mov_b32_e32 v251, 0x2400
	global_atomic_add v251, v0, s[94:95]
	global_atomic_add v251, v0, s[94:95] offset:256
	global_atomic_add v251, v0, s[94:95] offset:512
	global_atomic_add v251, v0, s[94:95] offset:768
	global_atomic_add v251, v0, s[94:95] offset:1024
	global_atomic_add v251, v0, s[94:95] offset:1280
	global_atomic_add v251, v0, s[94:95] offset:1536
	global_atomic_add v251, v0, s[94:95] offset:1792
	global_atomic_add v251, v0, s[94:95] offset:2048
	global_atomic_add v251, v0, s[94:95] offset:2304
	global_atomic_add v251, v0, s[94:95] offset:2560
	global_atomic_add v251, v0, s[94:95] offset:2816
	global_atomic_add v251, v0, s[94:95] offset:3072
	global_atomic_add v251, v0, s[94:95] offset:3328
	global_atomic_add v251, v0, s[94:95] offset:3584
	global_atomic_add v251, v0, s[94:95] offset:3840
.Lxb_norel_3:
.LBB0_429:
	s_or_b64 exec, exec, s[36:37]
	s_waitcnt vmcnt(0)

; __device__ __forceinline__ unsigned xb_ld(unsigned* p)              { return __hip_atomic_load(p, __ATOMIC_RELAXED, __HIP_MEMORY_SCOPE_AGENT); }
; __device__ __forceinline__ unsigned xb_add(unsigned* p, unsigned v) { return __hip_atomic_fetch_add(p, v, __ATOMIC_RELAXED, __HIP_MEMORY_SCOPE_AGENT); }
; #define XB_SPIN(cond, bar) do { unsigned _sp = 0; while (cond) { __builtin_amdgcn_s_sleep(1); \
;     if ((++_sp & 255u) == 0u) { if (xb_ld(&(bar)[XB_TMO])) break; if (_sp > XB_SPIN_CAP) { atomicAdd(&(bar)[XB_TMO], 1u); break; } } } } while (0)
; __device__ __forceinline__ void xcd_barrier(const XcdBarrier& b) {
;     ...
;         const unsigned old = xb_add(&bar[XB_XSUB(b.x)], 1u);
;         const unsigned gen = old / nloc;
;         if (old + 1u == (gen + 1u) * nloc) {
;     ...
;             XB_SPIN(xb_ld(&bar[XB_XGEN(b.x)]) == gen, bar);
.LBB0_537:
	s_or_b64 exec, exec, s[16:17]
	buffer_inv sc1
	v_cvt_f32_u32_e32 v5, v3
	s_waitcnt vmcnt(1)
	v_readfirstlane_b32 s16, v4
	v_sub_u32_e32 v4, 0, v3
	v_rcp_iflag_f32_e32 v5, v5
	v_add_u32_e32 v6, s16, v0
	v_mul_f32_e32 v5, 0x4f7ffffe, v5
	v_cvt_u32_f32_e32 v5, v5
	v_mul_lo_u32 v0, v4, v5
	v_mul_hi_u32 v0, v5, v0
	v_add_u32_e32 v0, v5, v0
	v_mul_hi_u32 v0, v6, v0
	v_mul_lo_u32 v4, v0, v3
	v_sub_u32_e32 v4, v6, v4
	v_add_u32_e32 v5, 1, v0
	v_cmp_ge_u32_e32 vcc, v4, v3
	s_nop 1
	v_cndmask_b32_e32 v0, v0, v5, vcc
	v_sub_u32_e32 v5, v4, v3
	v_cndmask_b32_e32 v4, v4, v5, vcc
	v_add_u32_e32 v5, 1, v0
	v_cmp_ge_u32_e32 vcc, v4, v3
	v_add_u32_e32 v4, 1, v6
	s_nop 0
	v_cndmask_b32_e32 v0, v0, v5, vcc
	v_mul_lo_u32 v5, v3, v0
	v_add_u32_e32 v3, v5, v3
	v_cmp_ne_u32_e32 vcc, v4, v3
	v_mov_b32_e32 v250, v0
	s_and_saveexec_b64 s[16:17], vcc
	s_xor_b64 s[36:37], exec, s[16:17]
	s_cbranch_execz .LBB0_551
	v_readlane_b32 s16, v245, 18
	v_readlane_b32 s17, v245, 19
	s_waitcnt lgkmcnt(0)
	s_nop 3
	global_load_dword v2, v1, s[16:17] sc1
	s_waitcnt vmcnt(0)
	v_cmp_eq_u32_e32 vcc, v2, v0
	s_and_saveexec_b64 s[40:41], vcc
	s_cbranch_execz .LBB0_550
	s_mov_b32 s23, 1
	s_mov_b64 s[42:43], 0
	s_branch .LBB0_541

; __device__ __forceinline__ unsigned xb_ld(unsigned* p)              { return __hip_atomic_load(p, __ATOMIC_RELAXED, __HIP_MEMORY_SCOPE_AGENT); }
; __device__ __forceinline__ unsigned xb_add(unsigned* p, unsigned v) { return __hip_atomic_fetch_add(p, v, __ATOMIC_RELAXED, __HIP_MEMORY_SCOPE_AGENT); }
; #define XB_SPIN(cond, bar) do { unsigned _sp = 0; while (cond) { __builtin_amdgcn_s_sleep(1); \
;     if ((++_sp & 255u) == 0u) { if (xb_ld(&(bar)[XB_TMO])) break; if (_sp > XB_SPIN_CAP) { atomicAdd(&(bar)[XB_TMO], 1u); break; } } } } while (0)
; __device__ __forceinline__ void xcd_barrier(const XcdBarrier& b) {
;     ...
;             const unsigned og = xb_add(&bar[XB_TOP], 1u);
;             const unsigned tg = og / nx;
;             if (og + 1u == (tg + 1u) * nx) xb_add(&bar[XB_TOPGEN], 1u);
;             else XB_SPIN(xb_ld(&bar[XB_TOPGEN]) == tg, bar);
.LBB0_554:
	s_or_b64 exec, exec, s[36:37]
	s_waitcnt vmcnt(0)
	v_readfirstlane_b32 s16, v3
	v_sub_u32_e32 v4, 0, v2
	s_mov_b64 s[40:41], -1
	v_add_u32_e32 v3, s16, v0
	v_cvt_f32_u32_e32 v0, v2
	v_readlane_b32 s16, v245, 22
	v_readlane_b32 s17, v245, 23
	v_rcp_iflag_f32_e32 v0, v0
	s_nop 0
	v_mul_f32_e32 v0, 0x4f7ffffe, v0
	v_cvt_u32_f32_e32 v0, v0
	v_mul_lo_u32 v4, v4, v0
	v_mul_hi_u32 v4, v0, v4
	v_add_u32_e32 v0, v0, v4
	v_mul_hi_u32 v0, v3, v0
	v_mul_lo_u32 v4, v0, v2
	v_sub_u32_e32 v4, v3, v4
	v_cmp_ge_u32_e32 vcc, v4, v2
	v_add_u32_e32 v5, 1, v0
	v_add_u32_e32 v3, 1, v3
	v_cndmask_b32_e32 v0, v0, v5, vcc
	v_sub_u32_e32 v5, v4, v2
	v_cndmask_b32_e32 v4, v4, v5, vcc
	v_cmp_ge_u32_e32 vcc, v4, v2
	v_add_u32_e32 v4, 1, v0
	s_nop 0
	v_cndmask_b32_e32 v0, v0, v4, vcc
	v_mul_lo_u32 v4, v2, v0
	v_add_u32_e32 v2, v4, v2
	v_cmp_ne_u32_e32 vcc, v3, v2
	s_mov_b64 s[98:99], vcc
	v_mov_b64_e32 v[2:3], s[16:17]
	s_and_saveexec_b64 s[36:37], vcc
	s_cbranch_execz .LBB0_566
	v_readlane_b32 s16, v245, 18
	v_readlane_b32 s17, v245, 19
	s_nop 4
	global_load_dword v2, v1, s[16:17] sc1
	s_mov_b64 s[16:17], 0
	s_waitcnt vmcnt(0)
	v_cmp_eq_u32_e32 vcc, v2, v250
	s_and_saveexec_b64 s[40:41], vcc
	s_cbranch_execz .LBB0_565
	s_mov_b32 s23, 1
	s_mov_b64 s[42:43], 0
	s_branch .LBB0_558

; __device__ __forceinline__ unsigned xb_ld(unsigned* p)              { return __hip_atomic_load(p, __ATOMIC_RELAXED, __HIP_MEMORY_SCOPE_AGENT); }
; #define XB_SPIN(cond, bar) do { unsigned _sp = 0; while (cond) { __builtin_amdgcn_s_sleep(1); \
;     if ((++_sp & 255u) == 0u) { if (xb_ld(&(bar)[XB_TMO])) break; if (_sp > XB_SPIN_CAP) { atomicAdd(&(bar)[XB_TMO], 1u); break; } } } } while (0)
; __device__ __forceinline__ void xcd_barrier(const XcdBarrier& b) {
;     ...
;             else XB_SPIN(xb_ld(&bar[XB_TOPGEN]) == tg, bar);
.LBB0_562:
	v_readlane_b32 s16, v245, 18
	v_readlane_b32 s17, v245, 19
	s_add_i32 s23, s23, 1
	s_mov_b64 s[48:49], -1
	s_nop 2
	global_load_dword v2, v1, s[16:17] sc1
	s_waitcnt vmcnt(0)
	v_cmp_ne_u32_e32 vcc, v2, v250
	s_orn2_b64 s[46:47], vcc, exec
	s_branch .LBB0_557

; __device__ __forceinline__ unsigned xb_ld(unsigned* p)              { return __hip_atomic_load(p, __ATOMIC_RELAXED, __HIP_MEMORY_SCOPE_AGENT); }
; __device__ __forceinline__ unsigned xb_add(unsigned* p, unsigned v) { return __hip_atomic_fetch_add(p, v, __ATOMIC_RELAXED, __HIP_MEMORY_SCOPE_AGENT); }
; #define XB_SPIN(cond, bar) do { unsigned _sp = 0; while (cond) { __builtin_amdgcn_s_sleep(1); \
;     if ((++_sp & 255u) == 0u) { if (xb_ld(&(bar)[XB_TMO])) break; if (_sp > XB_SPIN_CAP) { atomicAdd(&(bar)[XB_TMO], 1u); break; } } } } while (0)
; __device__ __forceinline__ void xcd_barrier(const XcdBarrier& b) {
;     ...
;         const unsigned old = xb_add(&bar[XB_XSUB(b.x)], 1u);
;         const unsigned gen = old / nloc;
;         if (old + 1u == (gen + 1u) * nloc) {
;     ...
;             XB_SPIN(xb_ld(&bar[XB_XGEN(b.x)]) == gen, bar);
.LBB0_752:
	s_or_b64 exec, exec, s[16:17]
	buffer_inv sc1
	v_cvt_f32_u32_e32 v5, v3
	s_waitcnt vmcnt(1)
	v_readfirstlane_b32 s16, v4
	v_sub_u32_e32 v4, 0, v3
	v_rcp_iflag_f32_e32 v5, v5
	v_add_u32_e32 v6, s16, v0
	v_mul_f32_e32 v5, 0x4f7ffffe, v5
	v_cvt_u32_f32_e32 v5, v5
	v_mul_lo_u32 v0, v4, v5
	v_mul_hi_u32 v0, v5, v0
	v_add_u32_e32 v0, v5, v0
	v_mul_hi_u32 v0, v6, v0
	v_mul_lo_u32 v4, v0, v3
	v_sub_u32_e32 v4, v6, v4
	v_add_u32_e32 v5, 1, v0
	v_cmp_ge_u32_e32 vcc, v4, v3
	s_nop 1
	v_cndmask_b32_e32 v0, v0, v5, vcc
	v_sub_u32_e32 v5, v4, v3
	v_cndmask_b32_e32 v4, v4, v5, vcc
	v_add_u32_e32 v5, 1, v0
	v_cmp_ge_u32_e32 vcc, v4, v3
	v_add_u32_e32 v4, 1, v6
	s_nop 0
	v_cndmask_b32_e32 v0, v0, v5, vcc
	v_mul_lo_u32 v5, v3, v0
	v_add_u32_e32 v3, v5, v3
	v_cmp_ne_u32_e32 vcc, v4, v3
	v_mov_b32_e32 v250, v0
	s_and_saveexec_b64 s[16:17], vcc
	s_xor_b64 s[18:19], exec, s[16:17]
	s_cbranch_execz .LBB0_766
	v_readlane_b32 s16, v245, 18
	v_readlane_b32 s17, v245, 19
	s_waitcnt lgkmcnt(0)
	s_nop 3
	global_load_dword v2, v1, s[16:17] sc1
	s_waitcnt vmcnt(0)
	v_cmp_eq_u32_e32 vcc, v2, v0
	s_and_saveexec_b64 s[20:21], vcc
	s_cbranch_execz .LBB0_765
	s_mov_b32 s42, 1
	s_mov_b64 s[22:23], 0
	s_branch .LBB0_756

; __device__ __forceinline__ unsigned xb_ld(unsigned* p)              { return __hip_atomic_load(p, __ATOMIC_RELAXED, __HIP_MEMORY_SCOPE_AGENT); }
; __device__ __forceinline__ unsigned xb_add(unsigned* p, unsigned v) { return __hip_atomic_fetch_add(p, v, __ATOMIC_RELAXED, __HIP_MEMORY_SCOPE_AGENT); }
; #define XB_SPIN(cond, bar) do { unsigned _sp = 0; while (cond) { __builtin_amdgcn_s_sleep(1); \
;     if ((++_sp & 255u) == 0u) { if (xb_ld(&(bar)[XB_TMO])) break; if (_sp > XB_SPIN_CAP) { atomicAdd(&(bar)[XB_TMO], 1u); break; } } } } while (0)
; __device__ __forceinline__ void xcd_barrier(const XcdBarrier& b) {
;     ...
;             const unsigned og = xb_add(&bar[XB_TOP], 1u);
;             const unsigned tg = og / nx;
;             if (og + 1u == (tg + 1u) * nx) xb_add(&bar[XB_TOPGEN], 1u);
;             else XB_SPIN(xb_ld(&bar[XB_TOPGEN]) == tg, bar);
.LBB0_769:
	s_or_b64 exec, exec, s[18:19]
	s_waitcnt vmcnt(0)
	v_readfirstlane_b32 s16, v3
	v_sub_u32_e32 v4, 0, v2
	s_mov_b64 s[20:21], -1
	v_add_u32_e32 v3, s16, v0
	v_cvt_f32_u32_e32 v0, v2
	v_readlane_b32 s16, v245, 22
	v_readlane_b32 s17, v245, 23
	v_rcp_iflag_f32_e32 v0, v0
	s_nop 0
	v_mul_f32_e32 v0, 0x4f7ffffe, v0
	v_cvt_u32_f32_e32 v0, v0
	v_mul_lo_u32 v4, v4, v0
	v_mul_hi_u32 v4, v0, v4
	v_add_u32_e32 v0, v0, v4
	v_mul_hi_u32 v0, v3, v0
	v_mul_lo_u32 v4, v0, v2
	v_sub_u32_e32 v4, v3, v4
	v_cmp_ge_u32_e32 vcc, v4, v2
	v_add_u32_e32 v5, 1, v0
	v_add_u32_e32 v3, 1, v3
	v_cndmask_b32_e32 v0, v0, v5, vcc
	v_sub_u32_e32 v5, v4, v2
	v_cndmask_b32_e32 v4, v4, v5, vcc
	v_cmp_ge_u32_e32 vcc, v4, v2
	v_add_u32_e32 v4, 1, v0
	s_nop 0
	v_cndmask_b32_e32 v0, v0, v4, vcc
	v_mul_lo_u32 v4, v2, v0
	v_add_u32_e32 v2, v4, v2
	v_cmp_ne_u32_e32 vcc, v3, v2
	s_mov_b64 s[98:99], vcc
	v_mov_b64_e32 v[2:3], s[16:17]
	s_and_saveexec_b64 s[18:19], vcc
	s_cbranch_execz .LBB0_781
	v_readlane_b32 s16, v245, 18
	v_readlane_b32 s17, v245, 19
	s_nop 4
	global_load_dword v2, v1, s[16:17] sc1
	s_mov_b64 s[16:17], 0
	s_waitcnt vmcnt(0)
	v_cmp_eq_u32_e32 vcc, v2, v250
	s_and_saveexec_b64 s[20:21], vcc
	s_cbranch_execz .LBB0_780
	s_mov_b32 s42, 1
	s_mov_b64 s[22:23], 0
	s_branch .LBB0_773

; __device__ __forceinline__ unsigned xb_ld(unsigned* p)              { return __hip_atomic_load(p, __ATOMIC_RELAXED, __HIP_MEMORY_SCOPE_AGENT); }
; #define XB_SPIN(cond, bar) do { unsigned _sp = 0; while (cond) { __builtin_amdgcn_s_sleep(1); \
;     if ((++_sp & 255u) == 0u) { if (xb_ld(&(bar)[XB_TMO])) break; if (_sp > XB_SPIN_CAP) { atomicAdd(&(bar)[XB_TMO], 1u); break; } } } } while (0)
; __device__ __forceinline__ void xcd_barrier(const XcdBarrier& b) {
;     ...
;             else XB_SPIN(xb_ld(&bar[XB_TOPGEN]) == tg, bar);
.LBB0_777:
	v_readlane_b32 s16, v245, 18
	v_readlane_b32 s17, v245, 19
	s_add_i32 s42, s42, 1
	s_mov_b64 s[40:41], -1
	s_nop 2
	global_load_dword v2, v1, s[16:17] sc1
	s_waitcnt vmcnt(0)
	v_cmp_ne_u32_e32 vcc, v2, v250
	s_orn2_b64 s[38:39], vcc, exec
	s_branch .LBB0_772

; __device__ __forceinline__ unsigned xb_ld(unsigned* p)              { return __hip_atomic_load(p, __ATOMIC_RELAXED, __HIP_MEMORY_SCOPE_AGENT); }
; __device__ __forceinline__ unsigned xb_add(unsigned* p, unsigned v) { return __hip_atomic_fetch_add(p, v, __ATOMIC_RELAXED, __HIP_MEMORY_SCOPE_AGENT); }
; #define XB_SPIN(cond, bar) do { unsigned _sp = 0; while (cond) { __builtin_amdgcn_s_sleep(1); \
;     if ((++_sp & 255u) == 0u) { if (xb_ld(&(bar)[XB_TMO])) break; if (_sp > XB_SPIN_CAP) { atomicAdd(&(bar)[XB_TMO], 1u); break; } } } } while (0)
; __device__ __forceinline__ void xcd_barrier(const XcdBarrier& b) {
;     ...
;             if (og + 1u == (tg + 1u) * nx) xb_add(&bar[XB_TOPGEN], 1u);
;             else XB_SPIN(xb_ld(&bar[XB_TOPGEN]) == tg, bar);
;             __builtin_amdgcn_fence(__ATOMIC_ACQUIRE, "agent");
;             xb_add(&bar[XB_XGEN(b.x)], 1u);
;             asm volatile("s_waitcnt vmcnt(0)" ::: "memory");
.LBB0_783:
	s_or_b64 exec, exec, s[16:17]
	s_mov_b64 s[16:17], exec
	v_mbcnt_lo_u32_b32 v0, s16, 0
	v_mbcnt_hi_u32_b32 v0, s17, v0
	v_cmp_eq_u32_e32 vcc, 0, v0
	s_waitcnt vmcnt(0)
	s_and_saveexec_b64 s[18:19], vcc
	s_cbranch_execz .LBB0_174
	s_bcnt1_i32_b64 s16, s[16:17]
	v_mov_b32_e32 v0, s16
	v_readlane_b32 s16, v245, 18
	v_readlane_b32 s17, v245, 19
	s_nop 4
	s_cmp_lg_u64 s[98:99], 0
	s_cbranch_scc1 .Lxb_norel_8
	v_mov_b32_e32 v251, 0x2400
	global_atomic_add v251, v0, s[94:95]
	global_atomic_add v251, v0, s[94:95] offset:256
	global_atomic_add v251, v0, s[94:95] offset:512
	global_atomic_add v251, v0, s[94:95] offset:768
	global_atomic_add v251, v0, s[94:95] offset:1024
	global_atomic_add v251, v0, s[94:95] offset:1280
	global_atomic_add v251, v0, s[94:95] offset:1536
	global_atomic_add v251, v0, s[94:95] offset:1792
	global_atomic_add v251, v0, s[94:95] offset:2048
	global_atomic_add v251, v0, s[94:95] offset:2304
	global_atomic_add v251, v0, s[94:95] offset:2560
	global_atomic_add v251, v0, s[94:95] offset:2816
	global_atomic_add v251, v0, s[94:95] offset:3072
	global_atomic_add v251, v0, s[94:95] offset:3328
	global_atomic_add v251, v0, s[94:95] offset:3584
	global_atomic_add v251, v0, s[94:95] offset:3840
.Lxb_norel_8:
	s_branch .LBB0_174

; __global__ void __launch_bounds__(512, 2) fwd_kernel(Args a) {
	.amdhsa_kernel _Z10fwd_kernel4Args
		.amdhsa_group_segment_fixed_size 0
		.amdhsa_private_segment_fixed_size 0
		.amdhsa_kernarg_size 416
		.amdhsa_user_sgpr_count 2
		.amdhsa_user_sgpr_dispatch_ptr 0
		.amdhsa_user_sgpr_queue_ptr 0
		.amdhsa_user_sgpr_kernarg_segment_ptr 1
		.amdhsa_user_sgpr_dispatch_id 0
		.amdhsa_user_sgpr_kernarg_preload_length 0
		.amdhsa_user_sgpr_kernarg_preload_offset 0
		.amdhsa_user_sgpr_private_segment_size 0
		.amdhsa_uses_dynamic_stack 0
		.amdhsa_enable_private_segment 0
		.amdhsa_system_sgpr_workgroup_id_x 1
		.amdhsa_system_sgpr_workgroup_id_y 0
		.amdhsa_system_sgpr_workgroup_id_z 0
		.amdhsa_system_sgpr_workgroup_info 0
		.amdhsa_system_vgpr_workitem_id 2
		.amdhsa_next_free_vgpr 252
		.amdhsa_next_free_sgpr 102
		.amdhsa_accum_offset 252
		.amdhsa_reserve_vcc 1
		.amdhsa_float_round_mode_32 0
		.amdhsa_float_round_mode_16_64 0
		.amdhsa_float_denorm_mode_32 3
		.amdhsa_float_denorm_mode_16_64 3
		.amdhsa_dx10_clamp 1
		.amdhsa_ieee_mode 1
		.amdhsa_fp16_overflow 0
		.amdhsa_tg_split 0
		.amdhsa_exception_fp_ieee_invalid_op 0
		.amdhsa_exception_fp_denorm_src 0
		.amdhsa_exception_fp_ieee_div_zero 0
		.amdhsa_exception_fp_ieee_overflow 0
		.amdhsa_exception_fp_ieee_underflow 0
		.amdhsa_exception_fp_ieee_inexact 0
		.amdhsa_exception_int_div_zero 0
	.end_amdhsa_kernel

; __global__ void __launch_bounds__(512, 2) fwd_kernel(Args a) {
amdhsa.kernels:
  - .agpr_count:     0
    .args:
      - .offset:         0
        .size:           160
        .value_kind:     by_value
      - .offset:         160
        .size:           4
        .value_kind:     hidden_block_count_x
      - .offset:         164
        .size:           4
        .value_kind:     hidden_block_count_y
      - .offset:         168
        .size:           4
        .value_kind:     hidden_block_count_z
      - .offset:         172
        .size:           2
        .value_kind:     hidden_group_size_x
      - .offset:         174
        .size:           2
        .value_kind:     hidden_group_size_y
      - .offset:         176
        .size:           2
        .value_kind:     hidden_group_size_z
      - .offset:         178
        .size:           2
        .value_kind:     hidden_remainder_x
      - .offset:         180
        .size:           2
        .value_kind:     hidden_remainder_y
      - .offset:         182
        .size:           2
        .value_kind:     hidden_remainder_z
      - .offset:         200
        .size:           8
        .value_kind:     hidden_global_offset_x
      - .offset:         208
        .size:           8
        .value_kind:     hidden_global_offset_y
      - .offset:         216
        .size:           8
        .value_kind:     hidden_global_offset_z
      - .offset:         224
        .size:           2
        .value_kind:     hidden_grid_dims
      - .offset:         248
        .size:           8
        .value_kind:     hidden_multigrid_sync_arg
      - .offset:         280
        .size:           4
        .value_kind:     hidden_dynamic_lds_size
    .group_segment_fixed_size: 0
    .kernarg_segment_align: 8
    .kernarg_segment_size: 416
    .language:       OpenCL C
    .language_version:
      - 2
      - 0
    .max_flat_workgroup_size: 512
    .name:           _Z10fwd_kernel4Args
    .private_segment_fixed_size: 0
    .sgpr_count:     108
    .sgpr_spill_count: 158
    .symbol:         _Z10fwd_kernel4Args.kd
    .uniform_work_group_size: 1
    .uses_dynamic_stack: false
    .vgpr_count:     252
    .vgpr_spill_count: 0
    .wavefront_size: 64
